# MLA norm1/norm2: xor-1 / xor-2 lane exchanges as quad_perm DPP moves instead of ds_bpermute round trips (bit-identical)
# speedup vs baseline: 1.0004x; 1.0004x over previous
.LBB0_1279:
	s_waitcnt vmcnt(6)
	v_mov_b32_e32 v56, v64
	v_mov_b32_e32 v57, v65
	v_mov_b32_e32 v58, v66
	v_mov_b32_e32 v59, v67
	v_mov_b32_e32 v86, v68
	v_mov_b32_e32 v87, v69
	v_mov_b32_e32 v88, v70
	v_mov_b32_e32 v89, v71
	v_mov_b32_e32 v77, v72
	v_mov_b32_e32 v78, v73
	v_mov_b32_e32 v79, v74
	v_mov_b32_e32 v80, v75
	v_mov_b32_e32 v81, v76
	v_lshl_add_u64 v[82:83], v[30:31], 0, s[20:21]
	v_lshl_add_u64 v[84:85], v[82:83], 0, v[18:19]
	global_load_dwordx4 v[64:67], v[84:85], off
	global_load_dwordx4 v[68:71], v[84:85], off offset:1024
	global_load_dwordx4 v[72:75], v[84:85], off offset:2048
	v_mov_b32_e32 v76, v25
	s_and_saveexec_b64 s[10:11], s[6:7]
	v_lshl_add_u64 v[84:85], v[82:83], 0, v[20:21]
	global_load_dword v76, v[84:85], off
	s_or_b64 exec, exec, s[10:11]
	v_mul_f32_e32 v14, v57, v57
	s_waitcnt lgkmcnt(0)
	v_mul_f32_e32 v15, v59, v59
	v_fmac_f32_e32 v14, v56, v56
	v_fmac_f32_e32 v15, v58, v58
	v_add_f32_e32 v24, v14, v15
	v_mov_b32_e32 v14, v86
	v_mov_b32_e32 v15, v87
	v_mov_b32_e32 v16, v88
	v_mov_b32_e32 v17, v89
	v_mul_f32_e32 v37, v15, v15
	v_mul_f32_e32 v55, v17, v17
	v_fmac_f32_e32 v37, v14, v14
	v_fmac_f32_e32 v55, v16, v16
	v_add_f32_e32 v37, v37, v55
	v_add_f32_e32 v24, v24, v37
	s_nop 1
	v_mov_b32_dpp v37, v24 quad_perm:[1,0,3,2] row_mask:0xf bank_mask:0xf bound_ctrl:1
	s_waitcnt lgkmcnt(0)
	v_add_f32_e32 v24, v24, v37
	s_nop 1
	v_mov_b32_dpp v37, v24 quad_perm:[2,3,0,1] row_mask:0xf bank_mask:0xf bound_ctrl:1
	s_waitcnt lgkmcnt(0)
	v_add_f32_e32 v24, v24, v37
	ds_bpermute_b32 v37, v46, v24
	s_waitcnt lgkmcnt(0)
	v_add_f32_e32 v24, v24, v37
	ds_bpermute_b32 v37, v47, v24
	s_waitcnt lgkmcnt(0)
	v_add_f32_e32 v24, v24, v37
	ds_bpermute_b32 v37, v48, v24
	s_waitcnt lgkmcnt(0)
	v_add_f32_e32 v24, v24, v37
	ds_bpermute_b32 v37, v49, v24
	s_waitcnt lgkmcnt(0)
	v_add_f32_e32 v24, v24, v37
	v_fmamk_f32 v24, v24, 0x3b000000, v51
	v_cmp_gt_f32_e32 vcc, s4, v24
	v_mul_f32_e32 v37, 0x4f800000, v24
	s_nop 0
	v_cndmask_b32_e32 v24, v24, v37, vcc
	v_sqrt_f32_e32 v37, v24
	s_nop 0
	v_add_u32_e32 v55, -1, v37
	v_fma_f32 v60, -v55, v37, v24
	v_cmp_ge_f32_e64 s[0:1], 0, v60
	v_add_u32_e32 v60, 1, v37
	s_nop 0
	v_cndmask_b32_e64 v55, v37, v55, s[0:1]
	v_fma_f32 v37, -v60, v37, v24
	v_cmp_lt_f32_e64 s[0:1], 0, v37
	s_nop 1
	v_cndmask_b32_e64 v37, v55, v60, s[0:1]
	v_mul_f32_e32 v55, 0x37800000, v37
	v_cndmask_b32_e32 v37, v37, v55, vcc
	v_cmp_class_f32_e32 vcc, v24, v52
	s_nop 1
	v_cndmask_b32_e32 v24, v37, v24, vcc
	v_div_scale_f32 v37, s[0:1], v24, v24, 1.0
	v_rcp_f32_e32 v55, v37
	s_nop 0
	v_fma_f32 v60, -v37, v55, 1.0
	v_fmac_f32_e32 v55, v60, v55
	v_div_scale_f32 v60, vcc, 1.0, v24, 1.0
	v_mul_f32_e32 v61, v60, v55
	v_fma_f32 v62, -v37, v61, v60
	v_fmac_f32_e32 v61, v62, v55
	v_fma_f32 v37, -v37, v61, v60
	v_div_fmas_f32 v37, v37, v55, v61
	v_div_fixup_f32 v24, v37, v24, 1.0
	v_mul_f32_e32 v37, v56, v24
	v_mul_f32_e32 v55, v57, v24
	v_mul_f32_e32 v37, v6, v37
	v_mul_f32_e32 v55, v7, v55
	v_mul_f32_e32 v14, v14, v24
	v_mul_f32_e32 v15, v15, v24
	v_cvt_pk_bf16_f32 v56, v37, v55
	v_mul_f32_e32 v37, v58, v24
	v_mul_f32_e32 v55, v59, v24
	v_lshl_add_u64 v[58:59], v[32:33], 0, v[34:35]
	v_mul_f32_e32 v14, v2, v14
	v_mul_f32_e32 v15, v3, v15
	v_mul_f32_e32 v37, v8, v37
	v_mul_f32_e32 v55, v9, v55
	v_cvt_pk_bf16_f32 v57, v37, v55
	global_store_dwordx2 v[58:59], v[56:57], off offset:-512
	v_cvt_pk_bf16_f32 v14, v14, v15
	v_mul_f32_e32 v15, v16, v24
	v_mul_f32_e32 v15, v4, v15
	v_mul_f32_e32 v16, v17, v24
	v_mul_f32_e32 v16, v5, v16
	v_cvt_pk_bf16_f32 v15, v15, v16
	global_store_dwordx2 v[58:59], v[14:15], off
	v_mov_b32_e32 v14, v77
	v_mov_b32_e32 v15, v78
	v_mov_b32_e32 v16, v79
	v_mov_b32_e32 v17, v80
	v_pk_mul_f32 v[40:41], v[16:17], v[16:17]
	v_pk_mul_f32 v[56:57], v[14:15], v[14:15]
	s_nop 0
	v_pk_mov_b32 v[58:59], v[56:57], v[40:41] op_sel:[1,0]
	v_mov_b32_e32 v57, v41
	v_pk_add_f32 v[40:41], v[58:59], v[56:57]
	s_nop 0
	v_add_f32_e32 v24, v40, v41
	s_nop 1
	v_mov_b32_dpp v37, v24 quad_perm:[1,0,3,2] row_mask:0xf bank_mask:0xf bound_ctrl:1
	s_waitcnt lgkmcnt(0)
	v_add_f32_e32 v24, v24, v37
	s_nop 1
	v_mov_b32_dpp v37, v24 quad_perm:[2,3,0,1] row_mask:0xf bank_mask:0xf bound_ctrl:1
	s_waitcnt lgkmcnt(0)
	v_add_f32_e32 v24, v24, v37
	ds_bpermute_b32 v37, v46, v24
	s_waitcnt lgkmcnt(0)
	v_add_f32_e32 v24, v24, v37
	ds_bpermute_b32 v37, v47, v24
	s_waitcnt lgkmcnt(0)
	v_add_f32_e32 v24, v24, v37
	ds_bpermute_b32 v37, v48, v24
	s_waitcnt lgkmcnt(0)
	v_add_f32_e32 v24, v24, v37
	ds_bpermute_b32 v37, v49, v24
	s_waitcnt lgkmcnt(0)
	v_add_f32_e32 v24, v24, v37
	v_fmamk_f32 v24, v24, 0x3b800000, v51
	v_cmp_gt_f32_e32 vcc, s4, v24
	v_mul_f32_e32 v37, 0x4f800000, v24
	s_nop 0
	v_cndmask_b32_e32 v24, v24, v37, vcc
	v_sqrt_f32_e32 v37, v24
	s_nop 0
	v_add_u32_e32 v40, -1, v37
	v_fma_f32 v41, -v40, v37, v24
	v_cmp_ge_f32_e64 s[0:1], 0, v41
	v_add_u32_e32 v41, 1, v37
	s_nop 0
	v_cndmask_b32_e64 v40, v37, v40, s[0:1]
	v_fma_f32 v37, -v41, v37, v24
	v_cmp_lt_f32_e64 s[0:1], 0, v37
	s_nop 1
	v_cndmask_b32_e64 v37, v40, v41, s[0:1]
	v_mul_f32_e32 v40, 0x37800000, v37
	v_cndmask_b32_e32 v37, v37, v40, vcc
	v_cmp_class_f32_e32 vcc, v24, v52
	s_nop 1
	v_cndmask_b32_e32 v24, v37, v24, vcc
	v_div_scale_f32 v37, s[0:1], v24, v24, 1.0
	v_rcp_f32_e32 v40, v37
	s_mov_b32 s0, 0x8000
	v_cmp_gt_i32_e64 s[0:1], s0, v22
	v_fma_f32 v41, -v37, v40, 1.0
	v_fmac_f32_e32 v40, v41, v40
	v_div_scale_f32 v41, vcc, 1.0, v24, 1.0
	v_mul_f32_e32 v55, v41, v40
	v_fma_f32 v56, -v37, v55, v41
	v_fmac_f32_e32 v55, v56, v40
	v_fma_f32 v37, -v37, v55, v41
	v_div_fmas_f32 v37, v37, v40, v55
	v_div_fixup_f32 v24, v37, v24, 1.0
	v_pk_mul_f32 v[14:15], v[14:15], v[24:25] op_sel_hi:[1,0]
	v_pk_mul_f32 v[16:17], v[16:17], v[24:25] op_sel_hi:[1,0]
	v_add_u32_e32 v24, 0xffff8000, v22
	v_lshlrev_b64 v[56:57], 10, v[24:25]
	v_lshl_add_u64 v[40:41], s[14:15], 0, v[34:35]
	v_lshl_add_u64 v[56:57], s[12:13], 0, v[56:57]
	v_cndmask_b32_e64 v41, v57, v41, s[0:1]
	v_cndmask_b32_e64 v40, v56, v40, s[0:1]
	v_pk_mul_f32 v[14:15], v[10:11], v[14:15]
	v_pk_mul_f32 v[16:17], v[12:13], v[16:17]
	v_lshl_add_u64 v[40:41], v[40:41], 0, v[38:39]
	global_store_dwordx4 v[40:41], v[14:17], off
	s_nop 1
	v_cvt_pk_bf16_f32 v14, v14, v15
	v_cvt_pk_bf16_f32 v15, v16, v17
	global_store_dwordx2 v[28:29], v[14:15], off
	v_mov_b32_e32 v14, v81
	v_mul_f32_e32 v15, v14, v14
	s_nop 1
	v_mov_b32_dpp v15, v15 quad_perm:[1,0,3,2] row_mask:0xf bank_mask:0xf bound_ctrl:1
	s_waitcnt lgkmcnt(0)
	v_fmac_f32_e32 v15, v14, v14
	s_nop 1
	v_mov_b32_dpp v16, v15 quad_perm:[2,3,0,1] row_mask:0xf bank_mask:0xf bound_ctrl:1
	s_waitcnt lgkmcnt(0)
	v_add_f32_e32 v15, v15, v16
	ds_bpermute_b32 v16, v46, v15
	s_waitcnt lgkmcnt(0)
	v_add_f32_e32 v15, v15, v16
	ds_bpermute_b32 v16, v47, v15
	s_waitcnt lgkmcnt(0)
	v_add_f32_e32 v15, v15, v16
	ds_bpermute_b32 v16, v48, v15
	s_waitcnt lgkmcnt(0)
	v_add_f32_e32 v15, v15, v16
	ds_bpermute_b32 v16, v49, v15
	s_waitcnt lgkmcnt(0)
	v_add_f32_e32 v15, v15, v16
	v_fmamk_f32 v15, v15, 0x3d000000, v51
	v_mul_f32_e32 v16, 0x4f800000, v15
	v_cmp_gt_f32_e32 vcc, s4, v15
	s_nop 1
	v_cndmask_b32_e32 v15, v15, v16, vcc
	v_sqrt_f32_e32 v16, v15
	s_nop 0
	v_add_u32_e32 v17, -1, v16
	v_add_u32_e32 v37, 1, v16
	v_fma_f32 v40, -v17, v16, v15
	v_fma_f32 v41, -v37, v16, v15
	v_cmp_ge_f32_e64 s[10:11], 0, v40
	s_nop 1
	v_cndmask_b32_e64 v16, v16, v17, s[10:11]
	v_cmp_lt_f32_e64 s[10:11], 0, v41
	s_nop 1
	v_cndmask_b32_e64 v16, v16, v37, s[10:11]
	v_mul_f32_e32 v17, 0x37800000, v16
	v_cndmask_b32_e32 v16, v16, v17, vcc
	v_cmp_class_f32_e32 vcc, v15, v52
	s_nop 1
	v_cndmask_b32_e32 v15, v16, v15, vcc
	v_div_scale_f32 v16, s[10:11], v15, v15, 1.0
	v_rcp_f32_e32 v17, v16
	v_div_scale_f32 v37, vcc, 1.0, v15, 1.0
	v_fma_f32 v40, -v16, v17, 1.0
	v_fmac_f32_e32 v17, v40, v17
	v_mul_f32_e32 v40, v37, v17
	v_fma_f32 v41, -v16, v40, v37
	v_fmac_f32_e32 v40, v41, v17
	v_fma_f32 v16, -v16, v40, v37
	v_div_fmas_f32 v16, v16, v17, v40
	v_div_fixup_f32 v15, v16, v15, 1.0
	v_mul_f32_e32 v14, v14, v15
	v_mul_f32_e32 v14, v42, v14
	ds_bpermute_b32 v15, v48, v14
	s_and_saveexec_b64 s[10:11], s[6:7]
	s_cbranch_execz .LBB0_1278
	v_ashrrev_i32_e32 v16, 31, v22
	v_lshrrev_b32_e32 v16, 21, v16
	v_add_u32_e32 v16, v22, v16
	v_and_b32_e32 v16, 0xfffff800, v16
	v_sub_u32_e32 v16, v22, v16
	v_cndmask_b32_e64 v16, v50, v16, s[0:1]
	v_cvt_f32_i32_e32 v16, v16
	v_readlane_b32 s72, v252, 12
	v_readlane_b32 s78, v252, 18
	v_readlane_b32 s79, v252, 19
	v_mul_f32_e32 v16, v43, v16
	v_mul_f32_e32 v17, 0.15915494, v16
	v_rndne_f32_e32 v17, v17
	v_fmac_f32_e32 v16, 0xc0c90000, v17
	v_fmac_f32_e32 v16, 0xbafdaa22, v17
	v_mul_f32_e32 v16, 0.15915494, v16
	v_cos_f32_e32 v17, v16
	v_sin_f32_e32 v16, v16
	v_mov_b32_e32 v37, v25
	v_readlane_b32 s73, v252, 13
	v_readlane_b32 s74, v252, 14
	s_waitcnt lgkmcnt(0)
	v_mul_f32_e32 v15, v16, v15
	v_cndmask_b32_e64 v40, v15, -v15, s[8:9]
	v_fmac_f32_e32 v40, v17, v14
	v_cndmask_b32_e64 v15, 0, v23, s[0:1]
	v_cndmask_b32_e64 v14, v24, v22, s[0:1]
	v_cndmask_b32_e64 v24, v53, v54, s[0:1]
	v_lshl_add_u64 v[16:17], s[78:79], 0, v[24:25]
	v_lshlrev_b64 v[14:15], 7, v[14:15]
	v_lshl_add_u64 v[14:15], v[16:17], 0, v[14:15]
	v_lshl_add_u64 v[14:15], v[14:15], 0, v[36:37]
	v_readlane_b32 s75, v252, 15
	v_readlane_b32 s76, v252, 16
	v_readlane_b32 s77, v252, 17
	global_store_dword v[14:15], v40, off
	v_cvt_pk_bf16_f32 v14, v40, v25
	global_store_short v[26:27], v14, off
	s_branch .LBB0_1278

.LBB0_1451:
	s_or_b64 exec, exec, s[0:1]
	s_nop 1
	v_mov_b32_e32 v42, v124
	v_mov_b32_e32 v43, v125
	v_mov_b32_e32 v44, v126
	v_mov_b32_e32 v45, v127
	v_mov_b32_e32 v46, v128
	v_mov_b32_e32 v47, v129
	v_mov_b32_e32 v48, v130
	v_mov_b32_e32 v49, v131
	v_add_u32_e32 v58, s60, v58
	v_add_u32_e32 v94, s4, v94
	v_add_u32_e32 v95, s5, v95
	v_lshl_add_u64 v[70:71], v[70:71], 0, s[10:11]
	v_lshl_add_u64 v[76:77], v[76:77], 0, s[14:15]
	v_lshl_add_u64 v[78:79], v[78:79], 0, s[10:11]
	v_lshlrev_b32_e32 v81, 16, v44
	v_lshlrev_b32_e32 v52, 16, v46
	v_and_b32_e32 v46, 0xffff0000, v46
	v_and_b32_e32 v97, 0xffff0000, v44
	v_mul_f32_e32 v44, v46, v46
	v_lshlrev_b32_e32 v53, 16, v47
	v_fmac_f32_e32 v44, v52, v52
	v_and_b32_e32 v47, 0xffff0000, v47
	v_fmac_f32_e32 v44, v53, v53
	v_lshlrev_b32_e32 v54, 16, v48
	v_fmac_f32_e32 v44, v47, v47
	v_and_b32_e32 v48, 0xffff0000, v48
	v_fmac_f32_e32 v44, v54, v54
	v_lshlrev_b32_e32 v55, 16, v49
	v_fmac_f32_e32 v44, v48, v48
	v_and_b32_e32 v49, 0xffff0000, v49
	v_fmac_f32_e32 v44, v55, v55
	v_lshlrev_b32_e32 v56, 16, v42
	v_fmac_f32_e32 v44, v49, v49
	v_and_b32_e32 v57, 0xffff0000, v42
	v_fmac_f32_e32 v44, v56, v56
	v_lshlrev_b32_e32 v64, 16, v43
	v_fmac_f32_e32 v44, v57, v57
	v_and_b32_e32 v80, 0xffff0000, v43
	v_fmac_f32_e32 v44, v64, v64
	v_fmac_f32_e32 v44, v80, v80
	v_fmac_f32_e32 v44, v81, v81
	v_and_b32_e32 v50, 0xffff0000, v45
	v_lshlrev_b32_e32 v51, 16, v45
	v_fmac_f32_e32 v44, v97, v97
	v_pk_mul_f32 v[42:43], v[50:51], v[50:51]
	s_nop 0
	v_add_f32_e32 v43, v43, v44
	v_add_f32_e32 v42, v42, v43
	s_nop 1
	v_mov_b32_dpp v43, v42 quad_perm:[1,0,3,2] row_mask:0xf bank_mask:0xf bound_ctrl:1
	s_waitcnt lgkmcnt(0)
	v_add_f32_e32 v42, v42, v43
	s_nop 1
	v_mov_b32_dpp v43, v42 quad_perm:[2,3,0,1] row_mask:0xf bank_mask:0xf bound_ctrl:1
	s_waitcnt lgkmcnt(0)
	v_add_f32_e32 v42, v42, v43
	v_fmamk_f32 v42, v42, 0x3c800000, v59
	v_cmp_gt_f32_e32 vcc, s18, v42
	v_mul_f32_e32 v43, 0x4f800000, v42
	s_nop 0
	v_cndmask_b32_e32 v42, v42, v43, vcc
	v_sqrt_f32_e32 v43, v42
	s_nop 0
	v_add_u32_e32 v44, -1, v43
	v_fma_f32 v45, -v44, v43, v42
	v_cmp_ge_f32_e64 s[0:1], 0, v45
	v_add_u32_e32 v45, 1, v43
	s_nop 0
	v_cndmask_b32_e64 v44, v43, v44, s[0:1]
	v_fma_f32 v43, -v45, v43, v42
	v_cmp_lt_f32_e64 s[0:1], 0, v43
	s_nop 1
	v_cndmask_b32_e64 v43, v44, v45, s[0:1]
	v_mul_f32_e32 v44, 0x37800000, v43
	v_cndmask_b32_e32 v43, v43, v44, vcc
	v_cmp_class_f32_e32 vcc, v42, v96
	s_nop 1
	v_cndmask_b32_e32 v42, v43, v42, vcc
	v_div_scale_f32 v43, s[0:1], v42, v42, 1.0
	v_rcp_f32_e32 v44, v43
	s_mov_b32 s0, 0x83ff
	v_fma_f32 v45, -v43, v44, 1.0
	v_fmac_f32_e32 v44, v45, v44
	v_div_scale_f32 v45, vcc, 1.0, v42, 1.0
	v_mul_f32_e32 v98, v45, v44
	v_fma_f32 v99, -v43, v98, v45
	v_fmac_f32_e32 v98, v99, v44
	v_fma_f32 v43, -v43, v98, v45
	v_div_fmas_f32 v43, v43, v44, v98
	v_div_fixup_f32 v98, v43, v42, 1.0
	v_mul_f32_e32 v42, v98, v52
	v_mul_f32_e32 v43, v98, v46
	v_mul_f32_e32 v42, v6, v42
	v_mul_f32_e32 v43, v7, v43
	v_cvt_pk_bf16_f32 v42, v42, v43
	v_mul_f32_e32 v43, v98, v53
	v_mul_f32_e32 v44, v98, v47
	v_mul_f32_e32 v43, v8, v43
	v_mul_f32_e32 v44, v9, v44
	v_cvt_pk_bf16_f32 v43, v43, v44
	v_mul_f32_e32 v44, v98, v54
	v_mul_f32_e32 v45, v98, v48
	v_mul_f32_e32 v44, v14, v44
	v_mul_f32_e32 v45, v15, v45
	v_cvt_pk_bf16_f32 v44, v44, v45
	v_mul_f32_e32 v45, v98, v55
	v_mul_f32_e32 v46, v98, v49
	v_mul_f32_e32 v45, v16, v45
	v_mul_f32_e32 v46, v17, v46
	v_cvt_pk_bf16_f32 v45, v45, v46
	v_mul_f32_e32 v46, v98, v56
	v_mul_f32_e32 v47, v98, v57
	v_mul_f32_e32 v46, v22, v46
	v_mul_f32_e32 v47, v23, v47
	v_cvt_pk_bf16_f32 v46, v46, v47
	v_mul_f32_e32 v47, v98, v64
	v_mul_f32_e32 v48, v98, v80
	v_mul_f32_e32 v47, v24, v47
	v_mul_f32_e32 v48, v25, v48
	v_cvt_pk_bf16_f32 v47, v47, v48
	v_mul_f32_e32 v48, v98, v81
	v_mul_f32_e32 v49, v98, v97
	v_mul_f32_e32 v48, v30, v48
	v_mul_f32_e32 v49, v31, v49
	v_cvt_pk_bf16_f32 v48, v48, v49
	v_mul_f32_e32 v49, v98, v51
	v_mul_f32_e32 v50, v98, v50
	v_mul_f32_e32 v49, v32, v49
	v_mul_f32_e32 v50, v33, v50
	v_cmp_lt_i32_e32 vcc, s0, v58
	v_cvt_pk_bf16_f32 v49, v49, v50
	v_lshl_add_u64 v[50:51], v[72:73], 0, v[62:63]
	v_lshl_add_u64 v[72:73], v[72:73], 0, s[12:13]
	s_or_b64 s[16:17], vcc, s[16:17]
	global_store_dwordx4 v[50:51], v[42:45], off offset:-16
	global_store_dwordx4 v[50:51], v[46:49], off
	s_andn2_b64 exec, exec, s[16:17]
	s_cbranch_execz .LBB0_1456
.LBB0_1452:
	s_waitcnt vmcnt(5)
	v_mov_b32_e32 v42, v100
	v_mov_b32_e32 v43, v101
	v_mov_b32_e32 v44, v102
	v_mov_b32_e32 v45, v103
	v_mov_b32_e32 v46, v104
	v_mov_b32_e32 v47, v105
	v_mov_b32_e32 v48, v106
	v_mov_b32_e32 v49, v107
	v_mov_b32_e32 v120, v108
	v_mov_b32_e32 v121, v109
	v_mov_b32_e32 v122, v110
	v_mov_b32_e32 v123, v111
	v_mov_b32_e32 v124, v112
	v_mov_b32_e32 v125, v113
	v_mov_b32_e32 v126, v114
	v_mov_b32_e32 v127, v115
	v_mov_b32_e32 v128, v116
	v_mov_b32_e32 v129, v117
	v_mov_b32_e32 v130, v118
	v_mov_b32_e32 v131, v119
	v_lshl_add_u64 v[134:135], v[78:79], 0, s[10:11]
	v_lshl_add_u64 v[136:137], v[76:77], 0, s[14:15]
	v_lshl_add_u64 v[132:133], v[134:135], 0, v[62:63]
	global_load_dwordx4 v[100:103], v[132:133], off offset:16
	global_load_dwordx4 v[104:107], v[132:133], off
	v_lshl_add_u64 v[132:133], v[134:135], 0, v[74:75]
	global_load_dwordx4 v[108:111], v[132:133], off
	v_lshl_add_u64 v[132:133], v[136:137], 0, v[62:63]
	global_load_dwordx4 v[112:115], v[132:133], off
	global_load_dwordx4 v[116:119], v[132:133], off offset:-16
	v_lshlrev_b32_e32 v97, 16, v44
	v_lshlrev_b32_e32 v50, 16, v46
	v_and_b32_e32 v46, 0xffff0000, v46
	v_and_b32_e32 v98, 0xffff0000, v44
	v_mul_f32_e32 v44, v46, v46
	v_lshlrev_b32_e32 v51, 16, v47
	v_fmac_f32_e32 v44, v50, v50
	v_and_b32_e32 v47, 0xffff0000, v47
	v_fmac_f32_e32 v44, v51, v51
	v_lshlrev_b32_e32 v52, 16, v48
	v_fmac_f32_e32 v44, v47, v47
	v_and_b32_e32 v48, 0xffff0000, v48
	v_fmac_f32_e32 v44, v52, v52
	v_lshlrev_b32_e32 v54, 16, v49
	v_fmac_f32_e32 v44, v48, v48
	v_and_b32_e32 v49, 0xffff0000, v49
	v_fmac_f32_e32 v44, v54, v54
	v_lshlrev_b32_e32 v55, 16, v42
	v_fmac_f32_e32 v44, v49, v49
	v_and_b32_e32 v56, 0xffff0000, v42
	v_fmac_f32_e32 v44, v55, v55
	v_lshlrev_b32_e32 v57, 16, v43
	v_fmac_f32_e32 v44, v56, v56
	v_and_b32_e32 v64, 0xffff0000, v43
	v_fmac_f32_e32 v44, v57, v57
	v_fmac_f32_e32 v44, v64, v64
	v_fmac_f32_e32 v44, v97, v97
	v_and_b32_e32 v80, 0xffff0000, v45
	v_lshlrev_b32_e32 v81, 16, v45
	v_fmac_f32_e32 v44, v98, v98
	v_pk_mul_f32 v[42:43], v[80:81], v[80:81]
	s_nop 0
	v_add_f32_e32 v43, v43, v44
	v_add_f32_e32 v42, v42, v43
	s_nop 1
	v_mov_b32_dpp v43, v42 quad_perm:[1,0,3,2] row_mask:0xf bank_mask:0xf bound_ctrl:1
	s_waitcnt lgkmcnt(0)
	v_add_f32_e32 v42, v42, v43
	s_nop 1
	v_mov_b32_dpp v43, v42 quad_perm:[2,3,0,1] row_mask:0xf bank_mask:0xf bound_ctrl:1
	s_waitcnt lgkmcnt(0)
	v_add_f32_e32 v42, v42, v43
	v_fmamk_f32 v42, v42, 0x3c800000, v59
	v_cmp_gt_f32_e32 vcc, s18, v42
	v_mul_f32_e32 v43, 0x4f800000, v42
	s_nop 0
	v_cndmask_b32_e32 v42, v42, v43, vcc
	v_sqrt_f32_e32 v43, v42
	s_nop 0
	v_add_u32_e32 v44, -1, v43
	v_fma_f32 v45, -v44, v43, v42
	v_cmp_ge_f32_e64 s[0:1], 0, v45
	v_add_u32_e32 v45, 1, v43
	s_nop 0
	v_cndmask_b32_e64 v44, v43, v44, s[0:1]
	v_fma_f32 v43, -v45, v43, v42
	v_cmp_lt_f32_e64 s[0:1], 0, v43
	s_nop 1
	v_cndmask_b32_e64 v43, v44, v45, s[0:1]
	v_mul_f32_e32 v44, 0x37800000, v43
	v_cndmask_b32_e32 v43, v43, v44, vcc
	v_cmp_class_f32_e32 vcc, v42, v96
	s_nop 1
	v_cndmask_b32_e32 v42, v43, v42, vcc
	v_div_scale_f32 v43, s[0:1], v42, v42, 1.0
	v_rcp_f32_e32 v44, v43
	s_movk_i32 s0, 0x7fff
	v_cmp_lt_i32_e64 s[8:9], s0, v58
	s_mov_b32 s0, 0x7ffffff0
	v_fma_f32 v45, -v43, v44, 1.0
	v_fmac_f32_e32 v44, v45, v44
	v_div_scale_f32 v45, vcc, 1.0, v42, 1.0
	v_mul_f32_e32 v53, v45, v44
	v_fma_f32 v99, -v43, v53, v45
	v_fmac_f32_e32 v53, v99, v44
	v_fma_f32 v43, -v43, v53, v45
	v_div_fmas_f32 v43, v43, v44, v53
	v_div_fixup_f32 v53, v43, v42, 1.0
	v_mul_f32_e32 v42, v53, v50
	v_mul_f32_e32 v43, v53, v46
	v_mul_f32_e32 v42, v2, v42
	v_mul_f32_e32 v43, v3, v43
	v_mul_f32_e32 v42, 0x3e16c740, v42
	v_mul_f32_e32 v43, 0x3e16c740, v43
	v_cvt_pk_bf16_f32 v46, v42, v43
	v_mul_f32_e32 v42, v6, v42
	v_mul_f32_e32 v43, v7, v43
	v_cvt_pk_bf16_f32 v42, v42, v43
	v_mul_f32_e32 v43, v53, v51
	v_mul_f32_e32 v44, v53, v47
	v_mul_f32_e32 v43, v4, v43
	v_mul_f32_e32 v44, v5, v44
	v_mul_f32_e32 v43, 0x3e16c740, v43
	v_mul_f32_e32 v44, 0x3e16c740, v44
	v_cvt_pk_bf16_f32 v47, v43, v44
	v_mul_f32_e32 v43, v8, v43
	v_mul_f32_e32 v44, v9, v44
	v_cvt_pk_bf16_f32 v43, v43, v44
	v_mul_f32_e32 v44, v53, v52
	v_mul_f32_e32 v45, v53, v48
	v_mul_f32_e32 v44, v10, v44
	v_mul_f32_e32 v45, v11, v45
	v_mul_f32_e32 v44, 0x3e16c740, v44
	v_mul_f32_e32 v45, 0x3e16c740, v45
	v_cvt_pk_bf16_f32 v48, v44, v45
	v_mul_f32_e32 v44, v14, v44
	v_mul_f32_e32 v45, v15, v45
	v_cvt_pk_bf16_f32 v50, v44, v45
	v_mul_f32_e32 v44, v53, v54
	v_mul_f32_e32 v45, v53, v49
	v_mul_f32_e32 v44, v12, v44
	v_mul_f32_e32 v45, v13, v45
	v_mul_f32_e32 v44, 0x3e16c740, v44
	v_mul_f32_e32 v45, 0x3e16c740, v45
	v_cvt_pk_bf16_f32 v49, v44, v45
	v_mul_f32_e32 v44, v16, v44
	v_mul_f32_e32 v45, v17, v45
	v_cvt_pk_bf16_f32 v51, v44, v45
	v_mul_f32_e32 v44, v53, v55
	v_mul_f32_e32 v45, v53, v56
	v_mul_f32_e32 v44, v18, v44
	v_mul_f32_e32 v45, v19, v45
	v_mul_f32_e32 v44, 0x3e16c740, v44
	v_mul_f32_e32 v45, 0x3e16c740, v45
	v_cvt_pk_bf16_f32 v54, v44, v45
	v_mul_f32_e32 v44, v22, v44
	v_mul_f32_e32 v45, v23, v45
	v_cvt_pk_bf16_f32 v44, v44, v45
	v_mul_f32_e32 v45, v53, v57
	v_mul_f32_e32 v52, v53, v64
	v_mul_f32_e32 v45, v20, v45
	v_mul_f32_e32 v52, v21, v52
	v_mul_f32_e32 v45, 0x3e16c740, v45
	v_mul_f32_e32 v52, 0x3e16c740, v52
	v_cvt_pk_bf16_f32 v55, v45, v52
	v_mul_f32_e32 v45, v24, v45
	v_mul_f32_e32 v52, v25, v52
	v_cvt_pk_bf16_f32 v45, v45, v52
	v_mul_f32_e32 v52, v53, v97
	v_mul_f32_e32 v56, v53, v98
	v_mul_f32_e32 v52, v26, v52
	v_mul_f32_e32 v56, v27, v56
	v_mul_f32_e32 v52, 0x3e16c740, v52
	v_mul_f32_e32 v57, 0x3e16c740, v56
	v_cvt_pk_bf16_f32 v56, v52, v57
	v_mul_f32_e32 v52, v30, v52
	v_mul_f32_e32 v57, v31, v57
	v_cvt_pk_bf16_f32 v52, v52, v57
	v_mul_f32_e32 v57, v53, v81
	v_mul_f32_e32 v53, v53, v80
	v_mul_f32_e32 v53, v29, v53
	v_mul_f32_e32 v57, v28, v57
	v_mul_f32_e32 v53, 0x3e16c740, v53
	v_mul_f32_e32 v64, 0x3e16c740, v57
	v_cvt_pk_bf16_f32 v57, v64, v53
	v_mul_f32_e32 v53, v33, v53
	v_lshl_add_u64 v[80:81], v[70:71], 0, v[62:63]
	v_mul_f32_e32 v64, v32, v64
	v_cvt_pk_bf16_f32 v53, v64, v53
	global_store_dwordx4 v[80:81], v[46:49], off
	global_store_dwordx4 v[80:81], v[54:57], off offset:16
	s_nop 0
	v_and_b32_e32 v47, 56, v95
	v_and_or_b32 v46, v94, s0, v90
	v_lshlrev_b32_e32 v64, 1, v47
	s_and_saveexec_b64 s[0:1], s[8:9]
	s_cbranch_execz .LBB0_1454
	v_mad_u64_u32 v[48:49], s[20:21], v46, 6, v[60:61]
	v_lshlrev_b64 v[48:49], 8, v[48:49]
	v_lshl_add_u64 v[48:49], s[50:51], 0, v[48:49]
	v_lshl_add_u64 v[48:49], v[48:49], 0, v[64:65]
	global_store_dwordx4 v[48:49], v[42:45], off
	global_store_dwordx4 v[48:49], v[50:53], off offset:128
.LBB0_1454:
	s_or_b64 exec, exec, s[0:1]
	v_mov_b32_e32 v42, v120
	v_mov_b32_e32 v43, v121
	v_mov_b32_e32 v44, v122
	v_mov_b32_e32 v45, v123
	v_and_b32_e32 v48, 0xffff0000, v42
	v_lshlrev_b32_e32 v47, 16, v42
	v_lshlrev_b32_e32 v51, 16, v44
	v_and_b32_e32 v52, 0xffff0000, v44
	v_mul_f32_e32 v44, v48, v48
	v_lshlrev_b32_e32 v49, 16, v43
	v_fmac_f32_e32 v44, v47, v47
	v_and_b32_e32 v50, 0xffff0000, v43
	v_fmac_f32_e32 v44, v49, v49
	v_fmac_f32_e32 v44, v50, v50
	v_fmac_f32_e32 v44, v51, v51
	v_lshlrev_b32_e32 v43, 16, v45
	v_fmac_f32_e32 v44, v52, v52
	v_and_b32_e32 v42, 0xffff0000, v45
	v_fmac_f32_e32 v44, v43, v43
	v_fmac_f32_e32 v44, v42, v42
	s_nop 1
	v_mov_b32_dpp v45, v44 quad_perm:[1,0,3,2] row_mask:0xf bank_mask:0xf bound_ctrl:1
	s_waitcnt lgkmcnt(0)
	v_add_f32_e32 v44, v44, v45
	s_nop 1
	v_mov_b32_dpp v45, v44 quad_perm:[2,3,0,1] row_mask:0xf bank_mask:0xf bound_ctrl:1
	s_waitcnt lgkmcnt(0)
	v_add_f32_e32 v44, v44, v45
	v_fmamk_f32 v44, v44, 0x3d000000, v59
	v_cmp_gt_f32_e32 vcc, s18, v44
	v_mul_f32_e32 v45, 0x4f800000, v44
	s_nop 0
	v_cndmask_b32_e32 v44, v44, v45, vcc
	v_sqrt_f32_e32 v45, v44
	s_nop 0
	v_add_u32_e32 v53, -1, v45
	v_fma_f32 v54, -v53, v45, v44
	v_cmp_ge_f32_e64 s[0:1], 0, v54
	v_add_u32_e32 v54, 1, v45
	s_nop 0
	v_cndmask_b32_e64 v53, v45, v53, s[0:1]
	v_fma_f32 v45, -v54, v45, v44
	v_cmp_lt_f32_e64 s[0:1], 0, v45
	s_nop 1
	v_cndmask_b32_e64 v45, v53, v54, s[0:1]
	v_mul_f32_e32 v53, 0x37800000, v45
	v_cndmask_b32_e32 v45, v45, v53, vcc
	v_cmp_class_f32_e32 vcc, v44, v96
	s_nop 1
	v_cndmask_b32_e32 v44, v45, v44, vcc
	v_div_scale_f32 v45, s[0:1], v44, v44, 1.0
	v_rcp_f32_e32 v53, v45
	s_mov_b32 s0, 0x8000
	v_fma_f32 v54, -v45, v53, 1.0
	v_fmac_f32_e32 v53, v54, v53
	v_div_scale_f32 v54, vcc, 1.0, v44, 1.0
	v_mul_f32_e32 v55, v54, v53
	v_fma_f32 v56, -v45, v55, v54
	v_fmac_f32_e32 v55, v56, v53
	v_fma_f32 v45, -v45, v55, v54
	v_div_fmas_f32 v45, v45, v53, v55
	v_div_fixup_f32 v44, v45, v44, 1.0
	v_ashrrev_i32_e32 v45, 31, v58
	v_lshrrev_b32_e32 v45, 21, v45
	v_add_u32_e32 v45, v58, v45
	v_and_b32_e32 v45, 0xfffff800, v45
	v_cmp_gt_i32_e32 vcc, s0, v58
	v_sub_u32_e32 v45, v58, v45
	v_mul_f32_e32 v47, v44, v47
	v_cndmask_b32_e32 v45, v93, v45, vcc
	v_mul_f32_e32 v53, v34, v47
	v_cvt_f32_i32_e32 v47, v45
	s_nop 1
	v_mov_b32_dpp v54, v53 quad_perm:[2,3,0,1] row_mask:0xf bank_mask:0xf bound_ctrl:1
	v_mul_f32_e32 v48, v44, v48
	v_mul_f32_e32 v49, v44, v49
	v_mul_f32_e32 v45, v82, v47
	v_mul_f32_e32 v55, 0.15915494, v45
	v_rndne_f32_e32 v55, v55
	v_fmac_f32_e32 v45, 0xc0c90000, v55
	v_fmac_f32_e32 v45, 0xbafdaa22, v55
	v_mul_f32_e32 v45, 0.15915494, v45
	v_cos_f32_e32 v55, v45
	v_sin_f32_e32 v45, v45
	v_mul_f32_e32 v50, v44, v50
	v_mul_f32_e32 v51, v44, v51
	v_mul_f32_e32 v52, v44, v52
	s_waitcnt lgkmcnt(0)
	v_mul_f32_e32 v45, v45, v54
	v_cndmask_b32_e64 v45, v45, -v45, s[6:7]
	v_mul_f32_e32 v54, v83, v47
	v_fmac_f32_e32 v45, v55, v53
	v_mul_f32_e32 v55, 0.15915494, v54
	v_rndne_f32_e32 v55, v55
	v_fmac_f32_e32 v54, 0xc0c90000, v55
	v_mul_f32_e32 v53, v35, v48
	v_fmac_f32_e32 v54, 0xbafdaa22, v55
	s_nop 1
	v_mov_b32_dpp v48, v53 quad_perm:[2,3,0,1] row_mask:0xf bank_mask:0xf bound_ctrl:1
	v_mul_f32_e32 v54, 0.15915494, v54
	v_cos_f32_e32 v55, v54
	v_sin_f32_e32 v54, v54
	v_mul_f32_e32 v52, v39, v52
	v_mul_f32_e32 v43, v44, v43
	v_mul_f32_e32 v43, v40, v43
	s_waitcnt lgkmcnt(0)
	v_mul_f32_e32 v48, v54, v48
	v_cndmask_b32_e64 v48, v48, -v48, s[6:7]
	v_mul_f32_e32 v54, v84, v47
	v_fmac_f32_e32 v48, v55, v53
	v_mul_f32_e32 v55, 0.15915494, v54
	v_rndne_f32_e32 v55, v55
	v_fmac_f32_e32 v54, 0xc0c90000, v55
	v_mul_f32_e32 v53, v36, v49
	v_fmac_f32_e32 v54, 0xbafdaa22, v55
	s_nop 1
	v_mov_b32_dpp v49, v53 quad_perm:[2,3,0,1] row_mask:0xf bank_mask:0xf bound_ctrl:1
	v_mul_f32_e32 v54, 0.15915494, v54
	v_cos_f32_e32 v55, v54
	v_sin_f32_e32 v54, v54
	v_mul_f32_e32 v42, v44, v42
	v_mul_f32_e32 v44, v89, v47
	v_mul_f32_e32 v42, v41, v42
	s_waitcnt lgkmcnt(0)
	v_mul_f32_e32 v49, v54, v49
	v_cndmask_b32_e64 v49, v49, -v49, s[6:7]
	v_mul_f32_e32 v54, v85, v47
	v_fmac_f32_e32 v49, v55, v53
	v_mul_f32_e32 v55, 0.15915494, v54
	v_rndne_f32_e32 v55, v55
	v_fmac_f32_e32 v54, 0xc0c90000, v55
	v_mul_f32_e32 v53, v37, v50
	v_fmac_f32_e32 v54, 0xbafdaa22, v55
	s_nop 1
	v_mov_b32_dpp v50, v53 quad_perm:[2,3,0,1] row_mask:0xf bank_mask:0xf bound_ctrl:1
	v_mul_f32_e32 v54, 0.15915494, v54
	v_cos_f32_e32 v55, v54
	v_sin_f32_e32 v54, v54
	s_waitcnt lgkmcnt(0)
	v_mul_f32_e32 v50, v54, v50
	v_cndmask_b32_e64 v50, v50, -v50, s[6:7]
	v_mul_f32_e32 v54, v86, v47
	v_fmac_f32_e32 v50, v55, v53
	v_mul_f32_e32 v55, 0.15915494, v54
	v_rndne_f32_e32 v55, v55
	v_fmac_f32_e32 v54, 0xc0c90000, v55
	v_mul_f32_e32 v53, v38, v51
	v_fmac_f32_e32 v54, 0xbafdaa22, v55
	s_nop 1
	v_mov_b32_dpp v51, v53 quad_perm:[2,3,0,1] row_mask:0xf bank_mask:0xf bound_ctrl:1
	v_mul_f32_e32 v54, 0.15915494, v54
	v_cos_f32_e32 v55, v54
	v_sin_f32_e32 v54, v54
	s_waitcnt lgkmcnt(0)
	v_mul_f32_e32 v51, v54, v51
	v_cndmask_b32_e64 v51, v51, -v51, s[6:7]
	v_mul_f32_e32 v54, v87, v47
	v_fmac_f32_e32 v51, v55, v53
	v_mul_f32_e32 v55, 0.15915494, v54
	v_rndne_f32_e32 v55, v55
	v_fmac_f32_e32 v54, 0xc0c90000, v55
	v_fmac_f32_e32 v54, 0xbafdaa22, v55
	s_nop 1
	v_mov_b32_dpp v53, v52 quad_perm:[2,3,0,1] row_mask:0xf bank_mask:0xf bound_ctrl:1
	v_mul_f32_e32 v54, 0.15915494, v54
	v_cos_f32_e32 v55, v54
	v_sin_f32_e32 v54, v54
	s_waitcnt lgkmcnt(0)
	v_mul_f32_e32 v53, v54, v53
	v_cndmask_b32_e64 v53, v53, -v53, s[6:7]
	v_mul_f32_e32 v54, v88, v47
	v_fmac_f32_e32 v53, v55, v52
	v_mul_f32_e32 v55, 0.15915494, v54
	v_rndne_f32_e32 v55, v55
	v_fmac_f32_e32 v54, 0xc0c90000, v55
	v_fmac_f32_e32 v54, 0xbafdaa22, v55
	s_nop 1
	v_mov_b32_dpp v52, v43 quad_perm:[2,3,0,1] row_mask:0xf bank_mask:0xf bound_ctrl:1
	v_mul_f32_e32 v54, 0.15915494, v54
	v_cos_f32_e32 v55, v54
	v_sin_f32_e32 v54, v54
	v_mul_f32_e32 v47, 0.15915494, v44
	v_rndne_f32_e32 v47, v47
	v_fmac_f32_e32 v44, 0xc0c90000, v47
	s_waitcnt lgkmcnt(0)
	v_mul_f32_e32 v52, v54, v52
	v_cndmask_b32_e64 v52, v52, -v52, s[6:7]
	v_fmac_f32_e32 v44, 0xbafdaa22, v47
	v_fmac_f32_e32 v52, v55, v43
	s_nop 1
	v_mov_b32_dpp v43, v42 quad_perm:[2,3,0,1] row_mask:0xf bank_mask:0xf bound_ctrl:1
	v_mul_f32_e32 v44, 0.15915494, v44
	v_cos_f32_e32 v47, v44
	v_sin_f32_e32 v44, v44
	s_waitcnt lgkmcnt(0)
	v_mul_f32_e32 v43, v44, v43
	v_cndmask_b32_e64 v54, v43, -v43, s[6:7]
	v_fmac_f32_e32 v54, v47, v42
	v_mul_f32_e32 v42, 0x3e16c740, v45
	v_mul_f32_e32 v43, 0x3e16c740, v48
	v_cvt_pk_bf16_f32 v42, v42, v43
	v_mul_f32_e32 v43, 0x3e16c740, v49
	v_mul_f32_e32 v44, 0x3e16c740, v50
	v_cvt_pk_bf16_f32 v43, v43, v44
	v_mul_f32_e32 v44, 0x3e16c740, v51
	v_mul_f32_e32 v45, 0x3e16c740, v53
	v_cvt_pk_bf16_f32 v44, v44, v45
	v_mul_f32_e32 v45, 0x3e16c740, v52
	v_lshl_add_u64 v[48:49], v[70:71], 0, v[74:75]
	v_mul_f32_e32 v47, 0x3e16c740, v54
	v_cvt_pk_bf16_f32 v45, v45, v47
	global_store_dwordx4 v[48:49], v[42:45], off
	s_and_saveexec_b64 s[0:1], s[8:9]
	s_cbranch_execz .LBB0_1451
	v_mad_u64_u32 v[46:47], s[8:9], v46, 6, v[66:67]
	v_lshlrev_b64 v[46:47], 8, v[46:47]
	v_lshl_add_u64 v[46:47], v[68:69], 0, v[46:47]
	v_lshl_add_u64 v[46:47], v[46:47], 0, v[64:65]
	global_store_dwordx4 v[46:47], v[42:45], off
	s_branch .LBB0_1451
